# cache-policy: nt on the f32 source loads of the phase-0 and phase-3 w_in conversions and of the phase-0 x row loads (streamed once), v123 base
# speedup vs baseline: 1.0053x; 1.0053x over previous
.LBB0_497:
	s_mul_hi_i32 s3, s2, 0x4bda12f7
	s_lshr_b32 s4, s3, 31
	s_ashr_i32 s3, s3, 6
	s_add_i32 s3, s3, s4
	s_lshl_b32 s50, s3, 6
	s_mulk_i32 s3, 0xe500
	s_add_i32 s3, s3, s0
	v_add_u32_e32 v8, s3, v44
	s_movk_i32 s4, 0x1ab0
	v_cmp_gt_i32_e64 s[38:39], s4, v8
	v_or_b32_e32 v20, s50, v45
	v_mov_b64_e32 v[10:11], s[18:19]
	s_movk_i32 s4, 0x6ac0
	v_mad_i64_i32 v[10:11], s[4:5], v20, s4, v[10:11]
	v_ashrrev_i32_e32 v9, 31, v8
	v_lshl_add_u64 v[24:25], v[8:9], 2, v[10:11]
	v_mov_b32_e32 v9, 0
	v_mov_b32_e32 v8, 0
	s_and_saveexec_b64 s[4:5], s[38:39]
	s_cbranch_execz .LBB0_499
	global_load_dword v8, v[24:25], off nt
.LBB0_499:
	s_or_b64 exec, exec, s[4:5]
	s_and_saveexec_b64 s[4:5], s[38:39]
	s_cbranch_execz .LBB0_501
	v_add_co_u32_e32 v10, vcc, 0xd000, v24
	s_nop 1
	v_addc_co_u32_e32 v11, vcc, 0, v25, vcc
	global_load_dword v9, v[10:11], off offset:1408 nt
.LBB0_501:
	s_or_b64 exec, exec, s[4:5]
	v_mov_b32_e32 v11, 0
	v_mov_b32_e32 v10, 0
	s_and_saveexec_b64 s[4:5], s[38:39]
	s_cbranch_execz .LBB0_503
	v_add_co_u32_e32 v12, vcc, 0x1a000, v24
	s_nop 1
	v_addc_co_u32_e32 v13, vcc, 0, v25, vcc
	global_load_dword v10, v[12:13], off offset:2816 nt
.LBB0_503:
	s_or_b64 exec, exec, s[4:5]
	s_and_saveexec_b64 s[4:5], s[38:39]
	s_cbranch_execz .LBB0_505
	v_add_co_u32_e32 v12, vcc, 0x28000, v24
	s_nop 1
	v_addc_co_u32_e32 v13, vcc, 0, v25, vcc
	global_load_dword v11, v[12:13], off offset:128 nt
.LBB0_505:
	s_or_b64 exec, exec, s[4:5]
	v_mov_b32_e32 v13, 0
	v_mov_b32_e32 v12, 0
	s_and_saveexec_b64 s[4:5], s[38:39]
	s_cbranch_execz .LBB0_507
	v_add_co_u32_e32 v14, vcc, 0x35000, v24
	s_nop 1
	v_addc_co_u32_e32 v15, vcc, 0, v25, vcc
	global_load_dword v12, v[14:15], off offset:1536 nt
.LBB0_507:
	s_or_b64 exec, exec, s[4:5]
	s_and_saveexec_b64 s[4:5], s[38:39]
	s_cbranch_execz .LBB0_509
	v_add_co_u32_e32 v14, vcc, 0x42000, v24
	s_nop 1
	v_addc_co_u32_e32 v15, vcc, 0, v25, vcc
	global_load_dword v13, v[14:15], off offset:2944 nt
.LBB0_509:
	s_or_b64 exec, exec, s[4:5]
	v_mov_b32_e32 v15, 0
	v_mov_b32_e32 v14, 0
	s_and_saveexec_b64 s[4:5], s[38:39]
	s_cbranch_execz .LBB0_511
	v_add_co_u32_e32 v16, vcc, 0x50000, v24
	s_nop 1
	v_addc_co_u32_e32 v17, vcc, 0, v25, vcc
	global_load_dword v14, v[16:17], off offset:256 nt
.LBB0_511:
	s_or_b64 exec, exec, s[4:5]
	s_and_saveexec_b64 s[4:5], s[38:39]
	s_cbranch_execz .LBB0_513
	v_add_co_u32_e32 v16, vcc, 0x5d000, v24
	s_nop 1
	v_addc_co_u32_e32 v17, vcc, 0, v25, vcc
	global_load_dword v15, v[16:17], off offset:1664 nt
.LBB0_513:
	s_or_b64 exec, exec, s[4:5]
	v_mov_b32_e32 v17, 0
	v_mov_b32_e32 v16, 0
	s_and_saveexec_b64 s[4:5], s[38:39]
	s_cbranch_execz .LBB0_515
	v_add_co_u32_e32 v18, vcc, 0x6a000, v24
	s_nop 1
	v_addc_co_u32_e32 v19, vcc, 0, v25, vcc
	global_load_dword v16, v[18:19], off offset:3072 nt
.LBB0_515:
	s_or_b64 exec, exec, s[4:5]
	s_and_saveexec_b64 s[4:5], s[38:39]
	s_cbranch_execz .LBB0_517
	v_add_co_u32_e32 v18, vcc, 0x78000, v24
	s_nop 1
	v_addc_co_u32_e32 v19, vcc, 0, v25, vcc
	global_load_dword v17, v[18:19], off offset:384 nt
.LBB0_517:
	s_or_b64 exec, exec, s[4:5]
	v_mov_b32_e32 v19, 0
	v_mov_b32_e32 v18, 0
	s_and_saveexec_b64 s[4:5], s[38:39]
	s_cbranch_execz .LBB0_519
	v_add_co_u32_e32 v22, vcc, 0x85000, v24
	s_nop 1
	v_addc_co_u32_e32 v23, vcc, 0, v25, vcc
	global_load_dword v18, v[22:23], off offset:1792 nt
.LBB0_519:
	s_or_b64 exec, exec, s[4:5]
	s_and_saveexec_b64 s[4:5], s[38:39]
	s_cbranch_execz .LBB0_521
	v_add_co_u32_e32 v22, vcc, 0x92000, v24
	s_nop 1
	v_addc_co_u32_e32 v23, vcc, 0, v25, vcc
	global_load_dword v19, v[22:23], off offset:3200 nt
.LBB0_521:
	s_or_b64 exec, exec, s[4:5]
	v_mov_b32_e32 v23, 0
	v_mov_b32_e32 v22, 0
	s_and_saveexec_b64 s[4:5], s[38:39]
	s_cbranch_execz .LBB0_523
	v_add_co_u32_e32 v26, vcc, 0xa0000, v24
	s_nop 1
	v_addc_co_u32_e32 v27, vcc, 0, v25, vcc
	global_load_dword v22, v[26:27], off offset:512 nt
.LBB0_523:
	s_or_b64 exec, exec, s[4:5]
	s_and_saveexec_b64 s[4:5], s[38:39]
	s_cbranch_execz .LBB0_525
	v_add_co_u32_e32 v26, vcc, 0xad000, v24
	s_nop 1
	v_addc_co_u32_e32 v27, vcc, 0, v25, vcc
	global_load_dword v23, v[26:27], off offset:1920 nt
.LBB0_525:
	s_or_b64 exec, exec, s[4:5]
	v_mov_b32_e32 v27, 0
	v_mov_b32_e32 v26, 0
	s_and_saveexec_b64 s[4:5], s[38:39]
	s_cbranch_execz .LBB0_527
	v_add_co_u32_e32 v28, vcc, 0xba000, v24
	s_nop 1
	v_addc_co_u32_e32 v29, vcc, 0, v25, vcc
	global_load_dword v26, v[28:29], off offset:3328 nt
.LBB0_527:
	s_or_b64 exec, exec, s[4:5]
	s_and_saveexec_b64 s[4:5], s[38:39]
	s_cbranch_execz .LBB0_529
	v_add_co_u32_e32 v28, vcc, 0xc8000, v24
	s_nop 1
	v_addc_co_u32_e32 v29, vcc, 0, v25, vcc
	global_load_dword v27, v[28:29], off offset:640 nt
.LBB0_529:
	s_or_b64 exec, exec, s[4:5]
	v_mov_b32_e32 v29, 0
	v_mov_b32_e32 v28, 0
	s_and_saveexec_b64 s[4:5], s[38:39]
	s_cbranch_execz .LBB0_531
	v_add_co_u32_e32 v30, vcc, 0xd5000, v24
	s_nop 1
	v_addc_co_u32_e32 v31, vcc, 0, v25, vcc
	global_load_dword v28, v[30:31], off offset:2048 nt
.LBB0_531:
	s_or_b64 exec, exec, s[4:5]
	s_and_saveexec_b64 s[4:5], s[38:39]
	s_cbranch_execz .LBB0_533
	v_add_co_u32_e32 v30, vcc, 0xe2000, v24
	s_nop 1
	v_addc_co_u32_e32 v31, vcc, 0, v25, vcc
	global_load_dword v29, v[30:31], off offset:3456 nt
.LBB0_533:
	s_or_b64 exec, exec, s[4:5]
	v_mov_b32_e32 v31, 0
	v_mov_b32_e32 v30, 0
	s_and_saveexec_b64 s[4:5], s[38:39]
	s_cbranch_execz .LBB0_535
	v_add_co_u32_e32 v32, vcc, 0xf0000, v24
	s_nop 1
	v_addc_co_u32_e32 v33, vcc, 0, v25, vcc
	global_load_dword v30, v[32:33], off offset:768 nt
.LBB0_535:
	s_or_b64 exec, exec, s[4:5]
	s_and_saveexec_b64 s[4:5], s[38:39]
	s_cbranch_execz .LBB0_537
	v_add_co_u32_e32 v32, vcc, 0xfd000, v24
	s_nop 1
	v_addc_co_u32_e32 v33, vcc, 0, v25, vcc
	global_load_dword v31, v[32:33], off offset:2176 nt
.LBB0_537:
	s_or_b64 exec, exec, s[4:5]
	v_mov_b32_e32 v33, 0
	v_mov_b32_e32 v32, 0
	s_and_saveexec_b64 s[4:5], s[38:39]
	s_cbranch_execz .LBB0_539
	v_add_co_u32_e32 v34, vcc, 0x10a000, v24
	s_nop 1
	v_addc_co_u32_e32 v35, vcc, 0, v25, vcc
	global_load_dword v32, v[34:35], off offset:3584 nt
.LBB0_539:
	s_or_b64 exec, exec, s[4:5]
	s_and_saveexec_b64 s[4:5], s[38:39]
	s_cbranch_execz .LBB0_541
	v_add_co_u32_e32 v34, vcc, 0x118000, v24
	s_nop 1
	v_addc_co_u32_e32 v35, vcc, 0, v25, vcc
	global_load_dword v33, v[34:35], off offset:896 nt
.LBB0_541:
	s_or_b64 exec, exec, s[4:5]
	v_mov_b32_e32 v35, 0
	v_mov_b32_e32 v34, 0
	s_and_saveexec_b64 s[4:5], s[38:39]
	s_cbranch_execz .LBB0_543
	v_add_co_u32_e32 v36, vcc, 0x125000, v24
	s_nop 1
	v_addc_co_u32_e32 v37, vcc, 0, v25, vcc
	global_load_dword v34, v[36:37], off offset:2304 nt
.LBB0_543:
	s_or_b64 exec, exec, s[4:5]
	s_and_saveexec_b64 s[4:5], s[38:39]
	s_cbranch_execz .LBB0_545
	v_add_co_u32_e32 v36, vcc, 0x132000, v24
	s_nop 1
	v_addc_co_u32_e32 v37, vcc, 0, v25, vcc
	global_load_dword v35, v[36:37], off offset:3712 nt
.LBB0_545:
	s_or_b64 exec, exec, s[4:5]
	v_mov_b32_e32 v37, 0
	v_mov_b32_e32 v36, 0
	s_and_saveexec_b64 s[4:5], s[38:39]
	s_cbranch_execz .LBB0_547
	v_add_co_u32_e32 v38, vcc, 0x140000, v24
	s_nop 1
	v_addc_co_u32_e32 v39, vcc, 0, v25, vcc
	global_load_dword v36, v[38:39], off offset:1024 nt
.LBB0_547:
	s_or_b64 exec, exec, s[4:5]
	s_and_saveexec_b64 s[4:5], s[38:39]
	s_cbranch_execz .LBB0_549
	v_add_co_u32_e32 v38, vcc, 0x14d000, v24
	s_nop 1
	v_addc_co_u32_e32 v39, vcc, 0, v25, vcc
	global_load_dword v37, v[38:39], off offset:2432 nt
.LBB0_549:
	s_or_b64 exec, exec, s[4:5]
	v_mov_b32_e32 v39, 0
	v_mov_b32_e32 v38, 0
	s_and_saveexec_b64 s[4:5], s[38:39]
	s_cbranch_execz .LBB0_551
	v_add_co_u32_e32 v40, vcc, 0x15a000, v24
	s_nop 1
	v_addc_co_u32_e32 v41, vcc, 0, v25, vcc
	global_load_dword v38, v[40:41], off offset:3840 nt
.LBB0_551:
	s_or_b64 exec, exec, s[4:5]
	s_and_saveexec_b64 s[4:5], s[38:39]
	s_cbranch_execz .LBB0_553
	v_add_co_u32_e32 v40, vcc, 0x168000, v24
	s_nop 1
	v_addc_co_u32_e32 v41, vcc, 0, v25, vcc
	global_load_dword v39, v[40:41], off offset:1152 nt
.LBB0_553:
	s_or_b64 exec, exec, s[4:5]
	v_mov_b32_e32 v41, 0
	v_mov_b32_e32 v40, 0
	s_and_saveexec_b64 s[4:5], s[38:39]
	s_cbranch_execz .LBB0_555
	v_add_co_u32_e32 v42, vcc, 0x175000, v24
	s_nop 1
	v_addc_co_u32_e32 v43, vcc, 0, v25, vcc
	global_load_dword v40, v[42:43], off offset:2560 nt
.LBB0_555:
	s_or_b64 exec, exec, s[4:5]
	s_and_saveexec_b64 s[4:5], s[38:39]
	s_cbranch_execz .LBB0_557
	v_add_co_u32_e32 v42, vcc, 0x182000, v24
	s_nop 1
	v_addc_co_u32_e32 v43, vcc, 0, v25, vcc
	global_load_dword v41, v[42:43], off offset:3968 nt
.LBB0_557:
	s_or_b64 exec, exec, s[4:5]
	v_mov_b32_e32 v43, 0
	v_mov_b32_e32 v42, 0
	s_and_saveexec_b64 s[4:5], s[38:39]
	s_cbranch_execz .LBB0_560
	v_add_co_u32_e32 v50, vcc, 0x190000, v24
	s_nop 1
	v_addc_co_u32_e32 v51, vcc, 0, v25, vcc
	global_load_dword v42, v[50:51], off offset:1280 nt
	s_or_b64 exec, exec, s[4:5]
	s_and_saveexec_b64 s[4:5], s[38:39]
	s_cbranch_execnz .LBB0_561

.LBB0_561:
	v_add_co_u32_e32 v24, vcc, 0x19d000, v24
	s_nop 1
	v_addc_co_u32_e32 v25, vcc, 0, v25, vcc
	global_load_dword v43, v[24:25], off offset:2688 nt
	s_or_b64 exec, exec, s[4:5]
	s_and_b64 vcc, exec, s[40:41]
	s_cbranch_vccz .LBB0_496

.LBB0_1151:
	s_mul_hi_i32 s4, s21, 0x4bda12f7
	s_lshr_b32 s5, s4, 31
	s_ashr_i32 s4, s4, 6
	s_add_i32 s4, s4, s5
	s_mul_i32 s23, s4, 0xffffe500
	s_add_i32 s23, s23, s0
	s_lshl_b32 s36, s4, 6
	v_add_u32_e32 v8, s23, v44
	s_movk_i32 s4, 0x1ab0
	v_cmp_gt_i32_e64 s[38:39], s4, v8
	v_or_b32_e32 v20, s36, v45
	v_mov_b64_e32 v[10:11], s[2:3]
	s_movk_i32 s4, 0x6ac0
	v_mad_i64_i32 v[10:11], s[4:5], v20, s4, v[10:11]
	v_ashrrev_i32_e32 v9, 31, v8
	v_lshl_add_u64 v[24:25], v[8:9], 2, v[10:11]
	v_mov_b32_e32 v9, 0
	v_mov_b32_e32 v8, 0
	s_and_saveexec_b64 s[4:5], s[38:39]
	s_cbranch_execz .LBB0_1153
	global_load_dword v8, v[24:25], off nt

.LBB0_1215:
	v_add_co_u32_e32 v24, vcc, 0x19d000, v24
	s_nop 1
	v_addc_co_u32_e32 v25, vcc, 0, v25, vcc
	global_load_dword v43, v[24:25], off offset:2688 nt
	s_or_b64 exec, exec, s[4:5]
	s_and_b64 vcc, exec, s[18:19]
	s_cbranch_vccz .LBB0_1150

.LBB0_1221:
	global_load_dwordx4 v[24:27], v[10:11], off nt
	v_add_u32_e32 v22, 0x100, v22
	v_cmp_lt_u32_e64 s[38:39], s28, v22
	v_lshl_add_u64 v[10:11], v[10:11], 0, s[16:17]
	s_or_b64 s[36:37], s[38:39], s[36:37]
	s_waitcnt vmcnt(0)
	v_pk_mul_f32 v[28:29], v[26:27], v[26:27]
	v_pk_mul_f32 v[30:31], v[24:25], v[24:25]
	v_cvt_pk_bf16_f32 v24, v24, v25
	v_cvt_pk_bf16_f32 v25, v26, v27
	v_pk_mov_b32 v[26:27], v[30:31], v[28:29] op_sel:[1,0]
	v_mov_b32_e32 v31, v29
	global_store_dwordx2 v[12:13], v[24:25], off offset:-4
	v_pk_add_f32 v[24:25], v[26:27], v[30:31]
	v_lshl_add_u64 v[12:13], v[12:13], 0, s[24:25]
	v_add_f32_e32 v23, v24, v25
	v_add_f32_e32 v21, v21, v23
	s_andn2_b64 exec, exec, s[36:37]
	s_cbranch_execnz .LBB0_1221
	s_or_b64 exec, exec, s[36:37]
	ds_bpermute_b32 v10, v14, v21
	s_ashr_i32 s19, s18, 31
	s_waitcnt lgkmcnt(0)
	v_add_f32_e32 v10, v21, v10
	ds_bpermute_b32 v11, v15, v10
	s_waitcnt lgkmcnt(0)
	v_add_f32_e32 v10, v10, v11
	ds_bpermute_b32 v11, v16, v10
	s_waitcnt lgkmcnt(0)
	v_add_f32_e32 v10, v10, v11
	ds_bpermute_b32 v11, v17, v10
	s_waitcnt lgkmcnt(0)
	v_add_f32_e32 v10, v10, v11
	ds_bpermute_b32 v11, v18, v10
	s_waitcnt lgkmcnt(0)
	v_add_f32_e32 v10, v10, v11
	ds_bpermute_b32 v11, v19, v10
	s_and_saveexec_b64 s[4:5], vcc
	s_cbranch_execz .LBB0_1219
	s_waitcnt lgkmcnt(0)
	v_add_f32_e32 v10, v10, v11
	v_mul_f32_e32 v10, 0x4b800000, v10
	v_trunc_f32_e32 v10, v10
	v_mul_f32_e32 v11, 0x2f800000, v10
	v_floor_f32_e32 v11, v11
	v_fmac_f32_e32 v10, 0xcf800000, v11
	v_cvt_u32_f32_e32 v10, v10
	v_cvt_u32_f32_e32 v11, v11
	s_lshl_b64 s[0:1], s[18:19], 3
	v_readlane_b32 s19, v255, 12
	s_add_u32 s0, s19, s0
	v_readlane_b32 s19, v255, 13
	s_addc_u32 s1, s19, s1
	global_store_dwordx2 v191, v[10:11], s[0:1]
	s_branch .LBB0_1219
